# P9 K-loop HID (A operand) LDS-DMA loads nt (on top of P8 deferred stores + sc1 nt)
# speedup vs baseline: 1.0113x; 1.0087x over previous
.LBB0_954:
	ds_read_b128 v[144:147], v151
	ds_read_b128 v[156:159], v151 offset:1024
	ds_read_b128 v[160:163], v151 offset:2048
	ds_read_b128 v[164:167], v151 offset:3072
	ds_read_b128 v[168:171], v152
	ds_read_b128 v[172:175], v152 offset:1024
	ds_read_b128 v[176:179], v152 offset:2048
	ds_read_b128 v[180:183], v152 offset:3072
	s_add_u32 s36, s34, 0x3fe000
	s_addc_u32 s37, s35, 0
	s_cmp_eq_u32 s55, 60
	s_cselect_b32 s39, s25, s37
	s_cselect_b32 s38, s31, s36
	s_cselect_b32 s37, s23, s54
	s_cselect_b32 s36, s52, s53
	v_lshl_add_u64 v[216:217], s[34:35], 0, v[136:137]
	s_add_i32 m0, s33, 0xc000
	ds_read_b128 v[184:187], v153
	ds_read_b128 v[188:191], v153 offset:1024
	ds_read_b128 v[192:195], v153 offset:2048
	ds_read_b128 v[196:199], v153 offset:3072
	ds_read_b128 v[200:203], v153 offset:4096
	ds_read_b128 v[204:207], v153 offset:5120
	ds_read_b128 v[208:211], v153 offset:6144
	ds_read_b128 v[212:215], v153 offset:7168
	global_load_lds_dwordx4 v[216:217], off nt
	v_lshl_add_u64 v[216:217], s[34:35], 0, v[138:139]
	s_add_i32 m0, s33, 0xe000
	s_nop 0
	global_load_lds_dwordx4 v[216:217], off nt
	s_waitcnt vmcnt(8)
	s_waitcnt lgkmcnt(0)
	s_barrier
	s_setprio 1
	s_waitcnt lgkmcnt(0)
	v_mfma_f32_16x16x32_bf16 v[124:127], v[144:147], v[184:187], v[124:127]
	v_mfma_f32_16x16x32_bf16 v[120:123], v[160:163], v[184:187], v[120:123]
	v_mfma_f32_16x16x32_bf16 v[108:111], v[144:147], v[192:195], v[108:111]
	v_mfma_f32_16x16x32_bf16 v[104:107], v[160:163], v[192:195], v[104:107]
	v_mfma_f32_16x16x32_bf16 v[92:95], v[144:147], v[200:203], v[92:95]
	v_mfma_f32_16x16x32_bf16 v[88:91], v[160:163], v[200:203], v[88:91]
	v_mfma_f32_16x16x32_bf16 v[76:79], v[144:147], v[208:211], v[76:79]
	v_mfma_f32_16x16x32_bf16 v[72:75], v[160:163], v[208:211], v[72:75]
	v_mfma_f32_16x16x32_bf16 v[124:127], v[156:159], v[188:191], v[124:127]
	v_mfma_f32_16x16x32_bf16 v[120:123], v[164:167], v[188:191], v[120:123]
	v_mfma_f32_16x16x32_bf16 v[108:111], v[156:159], v[196:199], v[108:111]
	v_mfma_f32_16x16x32_bf16 v[104:107], v[164:167], v[196:199], v[104:107]
	v_mfma_f32_16x16x32_bf16 v[92:95], v[156:159], v[204:207], v[92:95]
	v_mfma_f32_16x16x32_bf16 v[88:91], v[164:167], v[204:207], v[88:91]
	v_mfma_f32_16x16x32_bf16 v[76:79], v[156:159], v[212:215], v[76:79]
	v_mfma_f32_16x16x32_bf16 v[72:75], v[164:167], v[212:215], v[72:75]
	s_setprio 0
	s_setprio 1
	v_mfma_f32_16x16x32_bf16 v[116:119], v[168:171], v[184:187], v[116:119]
	v_mfma_f32_16x16x32_bf16 v[112:115], v[176:179], v[184:187], v[112:115]
	v_mfma_f32_16x16x32_bf16 v[100:103], v[168:171], v[192:195], v[100:103]
	v_mfma_f32_16x16x32_bf16 v[96:99], v[176:179], v[192:195], v[96:99]
	v_mfma_f32_16x16x32_bf16 v[84:87], v[168:171], v[200:203], v[84:87]
	v_mfma_f32_16x16x32_bf16 v[80:83], v[176:179], v[200:203], v[80:83]
	v_mfma_f32_16x16x32_bf16 v[68:71], v[168:171], v[208:211], v[68:71]
	v_mfma_f32_16x16x32_bf16 v[64:67], v[176:179], v[208:211], v[64:67]
	v_mfma_f32_16x16x32_bf16 v[116:119], v[172:175], v[188:191], v[116:119]
	v_mfma_f32_16x16x32_bf16 v[112:115], v[180:183], v[188:191], v[112:115]
	v_mfma_f32_16x16x32_bf16 v[100:103], v[172:175], v[196:199], v[100:103]
	v_mfma_f32_16x16x32_bf16 v[96:99], v[180:183], v[196:199], v[96:99]
	v_mfma_f32_16x16x32_bf16 v[84:87], v[172:175], v[204:207], v[84:87]
	v_mfma_f32_16x16x32_bf16 v[80:83], v[180:183], v[204:207], v[80:83]
	v_mfma_f32_16x16x32_bf16 v[68:71], v[172:175], v[212:215], v[68:71]
	v_mfma_f32_16x16x32_bf16 v[64:67], v[180:183], v[212:215], v[64:67]
	s_setprio 0
	s_barrier
	s_add_i32 s56, s49, s3
	v_lshl_add_u64 v[216:217], s[36:37], 0, v[130:131]
	s_mov_b32 m0, s56
	ds_read_b128 v[184:187], v153 offset:16384
	ds_read_b128 v[188:191], v153 offset:17408
	ds_read_b128 v[192:195], v153 offset:18432
	ds_read_b128 v[196:199], v153 offset:19456
	ds_read_b128 v[200:203], v153 offset:20480
	ds_read_b128 v[204:207], v153 offset:21504
	ds_read_b128 v[208:211], v153 offset:22528
	ds_read_b128 v[212:215], v153 offset:23552
	global_load_lds_dwordx4 v[216:217], off
	s_add_i32 m0, s56, 0x2000
	s_add_u32 s56, s36, 0x100000
	v_lshl_add_u64 v[218:219], s[36:37], 0, v[134:135]
	s_addc_u32 s57, s37, 0
	s_add_i32 s58, s50, s3
	global_load_lds_dwordx4 v[218:219], off
	v_lshl_add_u64 v[222:223], s[56:57], 0, v[130:131]
	s_mov_b32 m0, s58
	v_lshl_add_u64 v[224:225], s[38:39], 0, v[132:133]
	global_load_lds_dwordx4 v[222:223], off
	v_lshl_add_u64 v[222:223], s[56:57], 0, v[134:135]
	s_add_i32 m0, s58, 0x2000
	s_nop 0
	global_load_lds_dwordx4 v[222:223], off
	v_lshl_add_u64 v[222:223], s[38:39], 0, v[128:129]
	s_mov_b32 m0, s33
	s_nop 0
	global_load_lds_dwordx4 v[222:223], off nt
	s_mov_b32 m0, s40
	s_nop 0
	global_load_lds_dwordx4 v[224:225], off nt
	s_waitcnt vmcnt(8)
	s_waitcnt lgkmcnt(0)
	s_barrier
	s_setprio 1
	s_waitcnt lgkmcnt(0)
	v_mfma_f32_16x16x32_bf16 v[60:63], v[144:147], v[184:187], v[60:63]
	v_mfma_f32_16x16x32_bf16 v[56:59], v[160:163], v[184:187], v[56:59]
	v_mfma_f32_16x16x32_bf16 v[44:47], v[144:147], v[192:195], v[44:47]
	v_mfma_f32_16x16x32_bf16 v[40:43], v[160:163], v[192:195], v[40:43]
	v_mfma_f32_16x16x32_bf16 v[28:31], v[144:147], v[200:203], v[28:31]
	v_mfma_f32_16x16x32_bf16 v[24:27], v[160:163], v[200:203], v[24:27]
	v_mfma_f32_16x16x32_bf16 v[12:15], v[144:147], v[208:211], v[12:15]
	v_mfma_f32_16x16x32_bf16 v[8:11], v[160:163], v[208:211], v[8:11]
	v_mfma_f32_16x16x32_bf16 v[60:63], v[156:159], v[188:191], v[60:63]
	v_mfma_f32_16x16x32_bf16 v[56:59], v[164:167], v[188:191], v[56:59]
	v_mfma_f32_16x16x32_bf16 v[44:47], v[156:159], v[196:199], v[44:47]
	v_mfma_f32_16x16x32_bf16 v[40:43], v[164:167], v[196:199], v[40:43]
	v_mfma_f32_16x16x32_bf16 v[28:31], v[156:159], v[204:207], v[28:31]
	v_mfma_f32_16x16x32_bf16 v[24:27], v[164:167], v[204:207], v[24:27]
	v_mfma_f32_16x16x32_bf16 v[12:15], v[156:159], v[212:215], v[12:15]
	v_mfma_f32_16x16x32_bf16 v[8:11], v[164:167], v[212:215], v[8:11]
	s_setprio 0
	s_setprio 1
	v_mfma_f32_16x16x32_bf16 v[52:55], v[168:171], v[184:187], v[52:55]
	v_mfma_f32_16x16x32_bf16 v[48:51], v[176:179], v[184:187], v[48:51]
	v_mfma_f32_16x16x32_bf16 v[36:39], v[168:171], v[192:195], v[36:39]
	v_mfma_f32_16x16x32_bf16 v[32:35], v[176:179], v[192:195], v[32:35]
	v_mfma_f32_16x16x32_bf16 v[20:23], v[168:171], v[200:203], v[20:23]
	v_mfma_f32_16x16x32_bf16 v[16:19], v[176:179], v[200:203], v[16:19]
	v_mfma_f32_16x16x32_bf16 v[4:7], v[168:171], v[208:211], v[4:7]
	v_mfma_f32_16x16x32_bf16 v[0:3], v[176:179], v[208:211], v[0:3]
	v_mfma_f32_16x16x32_bf16 v[52:55], v[172:175], v[188:191], v[52:55]
	v_mfma_f32_16x16x32_bf16 v[48:51], v[180:183], v[188:191], v[48:51]
	v_mfma_f32_16x16x32_bf16 v[36:39], v[172:175], v[196:199], v[36:39]
	v_mfma_f32_16x16x32_bf16 v[32:35], v[180:183], v[196:199], v[32:35]
	v_mfma_f32_16x16x32_bf16 v[20:23], v[172:175], v[204:207], v[20:23]
	v_mfma_f32_16x16x32_bf16 v[16:19], v[180:183], v[204:207], v[16:19]
	v_mfma_f32_16x16x32_bf16 v[4:7], v[172:175], v[212:215], v[4:7]
	v_mfma_f32_16x16x32_bf16 v[0:3], v[180:183], v[212:215], v[0:3]
	s_setprio 0
	s_barrier
	s_add_i32 s56, 0, 0x18000
	v_add_u32_e32 v155, s56, v149
	s_add_i32 s57, 0, 0x1c000
	ds_read_b128 v[144:147], v155
	ds_read_b128 v[156:159], v155 offset:1024
	ds_read_b128 v[160:163], v155 offset:2048
	ds_read_b128 v[164:167], v155 offset:3072
	v_add_u32_e32 v155, s57, v149
	ds_read_b128 v[168:171], v155
	ds_read_b128 v[172:175], v155 offset:1024
	ds_read_b128 v[176:179], v155 offset:2048
	ds_read_b128 v[180:183], v155 offset:3072
	s_add_u32 s38, s38, 0x2000
	s_addc_u32 s39, s39, 0
	s_mov_b32 m0, s41
	v_lshl_add_u64 v[226:227], s[38:39], 0, v[128:129]
	ds_read_b128 v[184:187], v153 offset:32768
	ds_read_b128 v[188:191], v153 offset:33792
	ds_read_b128 v[192:195], v153 offset:34816
	ds_read_b128 v[196:199], v153 offset:35840
	ds_read_b128 v[200:203], v153 offset:36864
	ds_read_b128 v[204:207], v153 offset:37888
	ds_read_b128 v[208:211], v153 offset:38912
	ds_read_b128 v[212:215], v153 offset:39936
	global_load_lds_dwordx4 v[226:227], off nt
	v_lshl_add_u64 v[226:227], s[38:39], 0, v[132:133]
	s_mov_b32 m0, s42
	s_nop 0
	global_load_lds_dwordx4 v[226:227], off nt
	s_waitcnt vmcnt(8)
	s_waitcnt lgkmcnt(0)
	s_barrier
	s_setprio 1
	s_waitcnt lgkmcnt(0)
	v_mfma_f32_16x16x32_bf16 v[124:127], v[144:147], v[184:187], v[124:127]
	v_mfma_f32_16x16x32_bf16 v[120:123], v[160:163], v[184:187], v[120:123]
	v_mfma_f32_16x16x32_bf16 v[108:111], v[144:147], v[192:195], v[108:111]
	v_mfma_f32_16x16x32_bf16 v[104:107], v[160:163], v[192:195], v[104:107]
	v_mfma_f32_16x16x32_bf16 v[92:95], v[144:147], v[200:203], v[92:95]
	v_mfma_f32_16x16x32_bf16 v[88:91], v[160:163], v[200:203], v[88:91]
	v_mfma_f32_16x16x32_bf16 v[76:79], v[144:147], v[208:211], v[76:79]
	v_mfma_f32_16x16x32_bf16 v[72:75], v[160:163], v[208:211], v[72:75]
	v_mfma_f32_16x16x32_bf16 v[124:127], v[156:159], v[188:191], v[124:127]
	v_mfma_f32_16x16x32_bf16 v[120:123], v[164:167], v[188:191], v[120:123]
	v_mfma_f32_16x16x32_bf16 v[108:111], v[156:159], v[196:199], v[108:111]
	v_mfma_f32_16x16x32_bf16 v[104:107], v[164:167], v[196:199], v[104:107]
	v_mfma_f32_16x16x32_bf16 v[92:95], v[156:159], v[204:207], v[92:95]
	v_mfma_f32_16x16x32_bf16 v[88:91], v[164:167], v[204:207], v[88:91]
	v_mfma_f32_16x16x32_bf16 v[76:79], v[156:159], v[212:215], v[76:79]
	v_mfma_f32_16x16x32_bf16 v[72:75], v[164:167], v[212:215], v[72:75]
	s_setprio 0
	s_setprio 1
	v_mfma_f32_16x16x32_bf16 v[116:119], v[168:171], v[184:187], v[116:119]
	v_mfma_f32_16x16x32_bf16 v[112:115], v[176:179], v[184:187], v[112:115]
	v_mfma_f32_16x16x32_bf16 v[100:103], v[168:171], v[192:195], v[100:103]
	v_mfma_f32_16x16x32_bf16 v[96:99], v[176:179], v[192:195], v[96:99]
	v_mfma_f32_16x16x32_bf16 v[84:87], v[168:171], v[200:203], v[84:87]
	v_mfma_f32_16x16x32_bf16 v[80:83], v[176:179], v[200:203], v[80:83]
	v_mfma_f32_16x16x32_bf16 v[68:71], v[168:171], v[208:211], v[68:71]
	v_mfma_f32_16x16x32_bf16 v[64:67], v[176:179], v[208:211], v[64:67]
	v_mfma_f32_16x16x32_bf16 v[116:119], v[172:175], v[188:191], v[116:119]
	v_mfma_f32_16x16x32_bf16 v[112:115], v[180:183], v[188:191], v[112:115]
	v_mfma_f32_16x16x32_bf16 v[100:103], v[172:175], v[196:199], v[100:103]
	v_mfma_f32_16x16x32_bf16 v[96:99], v[180:183], v[196:199], v[96:99]
	v_mfma_f32_16x16x32_bf16 v[84:87], v[172:175], v[204:207], v[84:87]
	v_mfma_f32_16x16x32_bf16 v[80:83], v[180:183], v[204:207], v[80:83]
	v_mfma_f32_16x16x32_bf16 v[68:71], v[172:175], v[212:215], v[68:71]
	v_mfma_f32_16x16x32_bf16 v[64:67], v[180:183], v[212:215], v[64:67]
	s_setprio 0
	s_barrier
	s_add_i32 s38, s56, s3
	v_lshl_add_u64 v[216:217], v[216:217], 0, s[18:19]
	s_mov_b32 m0, s38
	ds_read_b128 v[184:187], v153 offset:49152
	ds_read_b128 v[188:191], v153 offset:50176
	ds_read_b128 v[192:195], v153 offset:51200
	ds_read_b128 v[196:199], v153 offset:52224
	ds_read_b128 v[200:203], v153 offset:53248
	ds_read_b128 v[204:207], v153 offset:54272
	ds_read_b128 v[208:211], v153 offset:55296
	ds_read_b128 v[212:215], v153 offset:56320
	global_load_lds_dwordx4 v[216:217], off
	s_add_i32 m0, s38, 0x2000
	s_add_u32 s36, s36, 0x100080
	v_lshl_add_u64 v[216:217], v[218:219], 0, s[18:19]
	s_addc_u32 s37, s37, 0
	s_add_i32 s38, s57, s3
	global_load_lds_dwordx4 v[216:217], off
	v_lshl_add_u64 v[216:217], s[36:37], 0, v[130:131]
	s_mov_b32 m0, s38
	s_nop 0
	global_load_lds_dwordx4 v[216:217], off
	v_lshl_add_u64 v[216:217], s[36:37], 0, v[134:135]
	s_add_i32 m0, s38, 0x2000
	s_nop 0
	global_load_lds_dwordx4 v[216:217], off
	v_lshl_add_u64 v[216:217], v[222:223], 0, s[98:99]
	s_mov_b32 m0, s46
	s_nop 0
	global_load_lds_dwordx4 v[216:217], off nt
	v_lshl_add_u64 v[216:217], v[224:225], 0, s[98:99]
	s_mov_b32 m0, s47
	s_nop 0
	global_load_lds_dwordx4 v[216:217], off nt
	s_waitcnt vmcnt(8)
	s_waitcnt lgkmcnt(0)
	s_barrier
	s_setprio 1
	s_waitcnt lgkmcnt(0)
	v_mfma_f32_16x16x32_bf16 v[60:63], v[144:147], v[184:187], v[60:63]
	v_mfma_f32_16x16x32_bf16 v[56:59], v[160:163], v[184:187], v[56:59]
	v_mfma_f32_16x16x32_bf16 v[44:47], v[144:147], v[192:195], v[44:47]
	v_mfma_f32_16x16x32_bf16 v[40:43], v[160:163], v[192:195], v[40:43]
	v_mfma_f32_16x16x32_bf16 v[28:31], v[144:147], v[200:203], v[28:31]
	v_mfma_f32_16x16x32_bf16 v[24:27], v[160:163], v[200:203], v[24:27]
	v_mfma_f32_16x16x32_bf16 v[12:15], v[144:147], v[208:211], v[12:15]
	v_mfma_f32_16x16x32_bf16 v[8:11], v[160:163], v[208:211], v[8:11]
	v_mfma_f32_16x16x32_bf16 v[60:63], v[156:159], v[188:191], v[60:63]
	v_mfma_f32_16x16x32_bf16 v[56:59], v[164:167], v[188:191], v[56:59]
	v_mfma_f32_16x16x32_bf16 v[44:47], v[156:159], v[196:199], v[44:47]
	v_mfma_f32_16x16x32_bf16 v[40:43], v[164:167], v[196:199], v[40:43]
	v_mfma_f32_16x16x32_bf16 v[28:31], v[156:159], v[204:207], v[28:31]
	v_mfma_f32_16x16x32_bf16 v[24:27], v[164:167], v[204:207], v[24:27]
	v_mfma_f32_16x16x32_bf16 v[12:15], v[156:159], v[212:215], v[12:15]
	v_mfma_f32_16x16x32_bf16 v[8:11], v[164:167], v[212:215], v[8:11]
	s_setprio 0
	s_setprio 1
	v_mfma_f32_16x16x32_bf16 v[52:55], v[168:171], v[184:187], v[52:55]
	v_mfma_f32_16x16x32_bf16 v[48:51], v[176:179], v[184:187], v[48:51]
	v_mfma_f32_16x16x32_bf16 v[36:39], v[168:171], v[192:195], v[36:39]
	v_mfma_f32_16x16x32_bf16 v[32:35], v[176:179], v[192:195], v[32:35]
	v_mfma_f32_16x16x32_bf16 v[20:23], v[168:171], v[200:203], v[20:23]
	v_mfma_f32_16x16x32_bf16 v[16:19], v[176:179], v[200:203], v[16:19]
	v_mfma_f32_16x16x32_bf16 v[4:7], v[168:171], v[208:211], v[4:7]
	v_mfma_f32_16x16x32_bf16 v[0:3], v[176:179], v[208:211], v[0:3]
	v_mfma_f32_16x16x32_bf16 v[52:55], v[172:175], v[188:191], v[52:55]
	v_mfma_f32_16x16x32_bf16 v[48:51], v[180:183], v[188:191], v[48:51]
	v_mfma_f32_16x16x32_bf16 v[36:39], v[172:175], v[196:199], v[36:39]
	v_mfma_f32_16x16x32_bf16 v[32:35], v[180:183], v[196:199], v[32:35]
	v_mfma_f32_16x16x32_bf16 v[20:23], v[172:175], v[204:207], v[20:23]
	v_mfma_f32_16x16x32_bf16 v[16:19], v[180:183], v[204:207], v[16:19]
	v_mfma_f32_16x16x32_bf16 v[4:7], v[172:175], v[212:215], v[4:7]
	v_mfma_f32_16x16x32_bf16 v[0:3], v[180:183], v[212:215], v[0:3]
	s_setprio 0
	s_barrier
	s_add_i32 s55, s55, 2
	s_add_u32 s34, s34, 0x800000
	s_addc_u32 s35, s35, 0
	s_add_u32 s53, s53, 0x100
	s_addc_u32 s54, s54, 0
	s_cmp_gt_u32 s55, 61
	s_cbranch_scc0 .LBB0_954
	s_and_b64 vcc, exec, s[20:21]
	s_cbranch_vccz .LBB0_957
	s_barrier
